# attention mainloop: one static s_setprio 1 for waves in odd hardware wave slots, per-tile priority flips removed
# baseline (speedup 1.0000x reference)
; __device__ __forceinline__ unsigned pack2bf(float a, float b) { const f32x2 v = {a, b}; return __builtin_bit_cast(unsigned, __builtin_convertvector(v, bf2_t)); }
; __device__ __forceinline__ void attn_unit(const Params& p, int b, int h, int q0, int nkeys, char* smem) {
;     ...
; #pragma unroll
;     for (int qs = 0; qs < 2; ++qs) {
;         float l = lrun[qs]; l += __shfl_xor(l, 16); l += __shfl_xor(l, 32);
;         const float rl = 1.f / l;
;         const size_t row = (size_t)b * TT + q0 + wid * 32 + qs * 16 + fr;
; #pragma unroll
;         for (int dv = 0; dv < 4; ++dv) {
;             uint2 w; w.x = pack2bf(o[dv][qs][0] * rl, o[dv][qs][1] * rl); w.y = pack2bf(o[dv][qs][2] * rl, o[dv][qs][3] * rl);
;             *(uint2*)(Y + row * 1024 + 256 + h * 64 + dv * 16 + fq * 4) = w;
;         }
;     }
.LBB0_447:
	s_setprio 0
	v_add_f32_e32 v118, v118, v119
	v_add_f32_e32 v119, v176, v177
	v_mbcnt_hi_u32_b32 v0, -1, v194
	v_and_b32_e32 v2, 64, v0
	v_xor_b32_e32 v1, 16, v0
	v_add_u32_e32 v2, 64, v2
	v_cmp_lt_i32_e32 vcc, v1, v2
	v_xor_b32_e32 v4, 32, v0
	v_ashrrev_i32_e32 v115, 31, v114
	v_cndmask_b32_e32 v1, v0, v1, vcc
	v_lshlrev_b32_e32 v3, 2, v1
	ds_bpermute_b32 v1, v3, v118
	v_cmp_lt_i32_e32 vcc, v4, v2
	v_mad_u32_u24 v104, s31, v204, v111
	v_mov_b32_e32 v117, v105
	v_cndmask_b32_e32 v0, v0, v4, vcc
	v_lshlrev_b32_e32 v10, 2, v0
	s_waitcnt lgkmcnt(0)
	v_add_f32_e32 v0, v118, v1
	ds_bpermute_b32 v1, v10, v0
	s_waitcnt lgkmcnt(0)
	v_add_f32_e32 v2, v0, v1
	v_div_scale_f32 v4, s[0:1], v2, v2, 1.0
	v_rcp_f32_e32 v5, v4
	v_lshl_add_u64 v[0:1], v[104:105], 0, v[114:115]
	s_lshl_b32 s0, s34, 6
	v_lshlrev_b64 v[0:1], 11, v[0:1]
	v_fma_f32 v6, -v4, v5, 1.0
	v_fmac_f32_e32 v5, v6, v5
	v_div_scale_f32 v6, vcc, 1.0, v2, 1.0
	v_mul_f32_e32 v7, v6, v5
	v_fma_f32 v8, -v4, v7, v6
	v_fmac_f32_e32 v7, v8, v5
	s_ashr_i32 s1, s0, 31
	v_fma_f32 v4, -v4, v7, v6
	v_lshl_add_u64 v[0:1], s[26:27], 0, v[0:1]
	v_div_fmas_f32 v4, v4, v5, v7
	v_lshl_add_u64 v[0:1], s[0:1], 1, v[0:1]
	v_div_fixup_f32 v2, v4, v2, 1.0
	v_lshl_add_u64 v[0:1], v[0:1], 0, v[116:117]
	s_mov_b64 s[0:1], 0x25f3200
	v_lshl_add_u64 v[4:5], v[0:1], 0, s[0:1]
	v_pk_mul_f32 v[6:7], v[92:93], v[2:3] op_sel_hi:[1,0]
	v_pk_mul_f32 v[8:9], v[94:95], v[2:3] op_sel_hi:[1,0]
	s_mov_b32 s0, 0x25f3000
	v_cvt_pk_bf16_f32 v6, v6, v7
	v_cvt_pk_bf16_f32 v7, v8, v9
	v_add_co_u32_e32 v8, vcc, s0, v0
	s_mov_b32 s34, s30
	s_nop 0
	v_addc_co_u32_e32 v9, vcc, 0, v1, vcc
	global_store_dwordx2 v[8:9], v[6:7], off offset:512
	v_pk_mul_f32 v[6:7], v[88:89], v[2:3] op_sel_hi:[1,0]
	v_pk_mul_f32 v[8:9], v[90:91], v[2:3] op_sel_hi:[1,0]
	ds_bpermute_b32 v3, v3, v119
	v_cvt_pk_bf16_f32 v6, v6, v7
	v_cvt_pk_bf16_f32 v7, v8, v9
	global_store_dwordx2 v[4:5], v[6:7], off offset:32
	s_waitcnt lgkmcnt(0)
	v_pk_mul_f32 v[6:7], v[80:81], v[2:3] op_sel_hi:[1,0]
	v_pk_mul_f32 v[8:9], v[82:83], v[2:3] op_sel_hi:[1,0]
	v_add_f32_e32 v3, v119, v3
	ds_bpermute_b32 v10, v10, v3
	v_cvt_pk_bf16_f32 v6, v6, v7
	v_cvt_pk_bf16_f32 v7, v8, v9
	global_store_dwordx2 v[4:5], v[6:7], off offset:64
	v_pk_mul_f32 v[6:7], v[72:73], v[2:3] op_sel_hi:[1,0]
	s_waitcnt lgkmcnt(0)
	v_add_f32_e32 v8, v3, v10
	v_div_scale_f32 v9, s[0:1], v8, v8, 1.0
	v_rcp_f32_e32 v10, v9
	v_pk_mul_f32 v[2:3], v[74:75], v[2:3] op_sel_hi:[1,0]
	v_cvt_pk_bf16_f32 v6, v6, v7
	v_cvt_pk_bf16_f32 v7, v2, v3
	v_fma_f32 v2, -v9, v10, 1.0
	v_fmac_f32_e32 v10, v2, v10
	v_div_scale_f32 v2, vcc, 1.0, v8, 1.0
	v_mul_f32_e32 v3, v2, v10
	global_store_dwordx2 v[4:5], v[6:7], off offset:96
	v_fma_f32 v4, -v9, v3, v2
	v_fmac_f32_e32 v3, v4, v10
	v_fma_f32 v2, -v9, v3, v2
	v_div_fmas_f32 v2, v2, v10, v3
	s_mov_b64 s[0:1], 0x25fb200
	v_div_fixup_f32 v2, v2, v8, 1.0
	v_lshl_add_u64 v[4:5], v[0:1], 0, s[0:1]
	s_mov_b32 s0, 0x25fb000
	v_pk_mul_f32 v[6:7], v[84:85], v[2:3] op_sel_hi:[1,0]
	v_pk_mul_f32 v[8:9], v[86:87], v[2:3] op_sel_hi:[1,0]
	v_add_co_u32_e32 v0, vcc, s0, v0
	v_cvt_pk_bf16_f32 v6, v6, v7
	v_cvt_pk_bf16_f32 v7, v8, v9
	v_addc_co_u32_e32 v1, vcc, 0, v1, vcc
	global_store_dwordx2 v[0:1], v[6:7], off offset:512
	v_pk_mul_f32 v[0:1], v[76:77], v[2:3] op_sel_hi:[1,0]
	v_pk_mul_f32 v[6:7], v[78:79], v[2:3] op_sel_hi:[1,0]
	v_cvt_pk_bf16_f32 v0, v0, v1
	v_cvt_pk_bf16_f32 v1, v6, v7
	global_store_dwordx2 v[4:5], v[0:1], off offset:32
	v_pk_mul_f32 v[0:1], v[68:69], v[2:3] op_sel_hi:[1,0]
	v_pk_mul_f32 v[6:7], v[70:71], v[2:3] op_sel_hi:[1,0]
	v_cvt_pk_bf16_f32 v0, v0, v1
	v_cvt_pk_bf16_f32 v1, v6, v7
	global_store_dwordx2 v[4:5], v[0:1], off offset:64
	v_pk_mul_f32 v[0:1], v[64:65], v[2:3] op_sel_hi:[1,0]
	v_pk_mul_f32 v[2:3], v[66:67], v[2:3] op_sel_hi:[1,0]
	v_cvt_pk_bf16_f32 v0, v0, v1
	v_cvt_pk_bf16_f32 v1, v2, v3
	global_store_dwordx2 v[4:5], v[0:1], off offset:96

; #define LSTOREX(P, st_) { LST1(st_, 0, P##k0) LST1(st_, 1, P##k1) LST1(st_, 2, P##k2) \
;                           *(uint4*)(smem + (st_) + KSZ + vdv * VROW + vcc * 16) = P##v0; *(uint4*)(smem + (st_) + KSZ + (vdv + 32) * VROW + vcc * 16) = P##v1; }
; __device__ __forceinline__ void attn_unit(const Params& p, int b, int h, int q0, int nkeys, char* smem) {
;     ...
;     bf16x8 qf[2][3];
; #pragma unroll
;     for (int qs = 0; qs < 2; ++qs)
; #pragma unroll
;         for (int s = 0; s < 3; ++s) qf[qs][s] = *(const bf16x8*)(Qg + (size_t)(q0 + wid * 32 + qs * 16 + fr) * 96 + s * 32 + fq * 8);
;     f32x4 o[4][2];
; #pragma unroll
;     for (int a = 0; a < 4; ++a)
; #pragma unroll
;         for (int c = 0; c < 2; ++c) o[a][c] = (f32x4){0.f, 0.f, 0.f, 0.f};
;     ...
;     uint4 ak0, ak1, ak2, av0, av1, bk0, bk1, bk2, bv0, bv1;
;     const int vdv = tid >> 3, vcc = tid & 7;
;     ...
;     const int nt = nkeys >> 6;
;     __syncthreads();
;     GLOADX(a, 0)
;     LSTOREX(a, 0)
;     GLOADX(a, 64)
;     __syncthreads();
.LBB0_458:
	s_lshl_b32 s0, s31, 3
	s_add_i32 s46, s34, s0
	v_mov_b32_e32 v64, v109
	s_mul_i32 s44, s46, 0xcc000
	v_readlane_b32 s0, v251, 56
	s_mul_hi_i32 s42, s46, 0xcc000
	v_and_b32_e32 v72, 15, v64
	v_bfe_u32 v28, v64, 4, 2
	v_readlane_b32 s1, v251, 57
	s_add_u32 s0, s0, s44
	v_ashrrev_i32_e32 v0, 1, v64
	s_addc_u32 s1, s1, s42
	v_readlane_b32 s4, v251, 58
	v_and_b32_e32 v114, 0xffffffe0, v0
	v_add_u32_e32 v111, s43, v72
	v_lshlrev_b32_e32 v104, 4, v28
	s_add_u32 s44, s4, s44
	v_add_u32_e32 v12, v111, v114
	s_waitcnt vmcnt(0)
	v_lshl_add_u64 v[8:9], s[0:1], 0, v[104:105]
	s_movk_i32 s4, 0xc0
	v_readlane_b32 s5, v251, 59
	v_mad_i64_i32 v[10:11], s[0:1], v12, s4, v[8:9]
	v_add_u32_e32 v12, 16, v12
	v_ashrrev_i32_e32 v65, 31, v64
	s_addc_u32 s45, s5, s42
	v_mad_i64_i32 v[20:21], s[0:1], v12, s4, v[8:9]
	v_lshlrev_b64 v[66:67], 4, v[64:65]
	s_mul_i32 s47, s46, 0x88000
	v_readlane_b32 s0, v251, 60
	v_lshl_add_u64 v[24:25], s[44:45], 0, v[66:67]
	s_movk_i32 s4, 0x2000
	s_mul_hi_i32 s42, s46, 0x88000
	s_add_u32 s0, s0, s47
	v_readlane_b32 s1, v251, 61
	v_add_co_u32_e32 v26, vcc, s4, v24
	global_load_dwordx4 v[0:3], v[10:11], off
	global_load_dwordx4 v[4:7], v[10:11], off offset:64
	s_nop 0
	global_load_dwordx4 v[8:11], v[10:11], off offset:128
	s_nop 0
	global_load_dwordx4 v[12:15], v[20:21], off
	global_load_dwordx4 v[16:19], v[20:21], off offset:64
	s_nop 0
	global_load_dwordx4 v[20:23], v[20:21], off offset:128
	s_barrier
	global_load_dwordx4 v[44:47], v[24:25], off
	s_addc_u32 s1, s1, s42
	v_addc_co_u32_e32 v27, vcc, 0, v25, vcc
	v_ashrrev_i32_e32 v65, 3, v64
	global_load_dwordx4 v[48:51], v[26:27], off offset:-4096
	global_load_dwordx4 v[52:55], v[26:27], off
	v_mov_b64_e32 v[26:27], s[0:1]
	s_movk_i32 s4, 0x2200
	v_lshlrev_b32_e32 v29, 4, v64
	v_mad_i64_i32 v[26:27], s[0:1], v65, s4, v[26:27]
	v_and_b32_e32 v68, 0x70, v29
	v_mov_b32_e32 v69, v105
	v_lshl_add_u64 v[32:33], v[26:27], 0, v[68:69]
	s_mov_b32 s0, 0x44000
	v_add_co_u32_e32 v40, vcc, s0, v32
	s_movk_i32 s0, 0x4000
	s_nop 0
	v_addc_co_u32_e32 v41, vcc, 0, v33, vcc
	v_lshlrev_b32_e32 v116, 3, v28
	v_add_co_u32_e32 v28, vcc, s0, v24
	s_movk_i32 s0, 0x5000
	s_nop 0
	v_addc_co_u32_e32 v29, vcc, 0, v25, vcc
	v_add_co_u32_e32 v36, vcc, s0, v24
	global_load_dwordx4 v[56:59], v[32:33], off
	global_load_dwordx4 v[60:63], v[40:41], off
	v_addc_co_u32_e32 v37, vcc, 0, v25, vcc
	global_load_dwordx4 v[24:27], v[28:29], off offset:-4096
	s_nop 0
	global_load_dwordx4 v[28:31], v[28:29], off
	s_nop 0
	global_load_dwordx4 v[32:35], v[32:33], off offset:128
	s_nop 0
	global_load_dwordx4 v[36:39], v[36:37], off
	s_nop 0
	global_load_dwordx4 v[40:43], v[40:41], off offset:128
	s_mov_b32 s5, 0x2aaaaaab
	v_mul_hi_i32 v69, v64, s5
	v_lshrrev_b32_e32 v74, 31, v69
	v_ashrrev_i32_e32 v69, 1, v69
	v_mad_i64_i32 v[70:71], s[0:1], v65, s4, 0
	v_add_u32_e32 v69, v69, v74
	v_mul_lo_u32 v76, v69, -12
	s_movk_i32 s0, 0xd0
	v_add_u32_e32 v73, 0x100, v64
	v_mul_lo_u32 v69, v69, s0
	v_add_lshl_u32 v76, v76, v64, 4
	v_mul_hi_i32 v75, v73, s5
	v_add_u32_e32 v115, v69, v76
	v_lshrrev_b32_e32 v74, 31, v75
	v_mov_b32_e32 v92, 0
	s_mov_b32 s42, 3
	v_mov_b32_e32 v93, v92
	v_mov_b32_e32 v94, v92
	v_mov_b32_e32 v95, v92
	v_mov_b32_e32 v84, v92
	v_mov_b32_e32 v85, v92
	v_mov_b32_e32 v86, v92
	v_mov_b32_e32 v87, v92
	v_mov_b32_e32 v88, v92
	v_mov_b32_e32 v89, v92
	v_mov_b32_e32 v90, v92
	v_mov_b32_e32 v91, v92
	v_mov_b32_e32 v76, v92
	v_mov_b32_e32 v77, v92
	v_mov_b32_e32 v78, v92
	v_mov_b32_e32 v79, v92
	v_mov_b32_e32 v80, v92
	v_mov_b32_e32 v81, v92
	v_mov_b32_e32 v82, v92
	v_mov_b32_e32 v83, v92
	v_mov_b32_e32 v69, v92
	v_mov_b32_e32 v118, v92
	v_mov_b32_e32 v119, v92
	s_waitcnt vmcnt(9)
	ds_write_b128 v115, v[44:47]
	v_ashrrev_i32_e32 v44, 1, v75
	v_add_u32_e32 v44, v44, v74
	v_mul_lo_u32 v45, v44, -12
	v_mul_lo_u32 v44, v44, s0
	v_add_lshl_u32 v45, v45, v73, 4
	v_add_u32_e32 v117, v44, v45
	v_add_u32_e32 v44, 0x200, v64
	v_mul_hi_i32 v45, v44, s5
	v_lshrrev_b32_e32 v46, 31, v45
	v_ashrrev_i32_e32 v45, 1, v45
	v_add_u32_e32 v45, v45, v46
	v_mul_lo_u32 v46, v45, -12
	v_mul_lo_u32 v45, v45, s0
	v_add_lshl_u32 v44, v46, v44, 4
	s_movk_i32 s0, 0x90
	v_add_u32_e32 v217, v45, v44
	v_mul_lo_u32 v44, v65, s0
	v_add_u32_e32 v218, v44, v68
	v_sub_u32_e32 v44, v104, v116
	v_mul_u32_u24_e32 v45, 0xd0, v72
	v_mul_u32_u24_e32 v46, 0x90, v72
	v_mad_i64_i32 v[120:121], s[0:1], s46, v200, v[70:71]
	v_or_b32_e32 v120, v120, v68
	v_mad_i64_i32 v[122:123], s[0:1], s46, v203, v[66:67]
	v_add_u32_e32 v104, v104, v45
	v_add_u32_e32 v219, v44, v46
	v_mov_b32_e32 v68, v92
	v_mov_b32_e32 v70, v92
	v_mov_b32_e32 v71, v92
	v_mov_b32_e32 v72, v92
	v_mov_b32_e32 v73, v92
	v_mov_b32_e32 v74, v92
	v_mov_b32_e32 v75, v92
	v_mov_b32_e32 v64, v92
	v_mov_b32_e32 v65, v92
	v_mov_b32_e32 v66, v92
	v_mov_b32_e32 v67, v92
	s_waitcnt vmcnt(8)
	ds_write_b128 v117, v[48:51]
	s_waitcnt vmcnt(7)
	ds_write_b128 v217, v[52:55]
	s_waitcnt vmcnt(6)
	ds_write_b128 v218, v[56:59] offset:13312
	s_waitcnt vmcnt(5)
	ds_write_b128 v218, v[60:63] offset:17920
	s_waitcnt lgkmcnt(0)
	s_barrier
	v_add_u32_e32 v178, 0x3400, v219
	v_add_u32_e32 v179, 0x3d00, v219
	v_add_u32_e32 v191, 0x4600, v219
	v_add_u32_e32 v208, 0x4f00, v219
	v_add_u32_e32 v209, 0x8c00, v219
	v_add_u32_e32 v210, 0x9500, v219
	v_add_u32_e32 v211, 0x9e00, v219
	v_add_u32_e32 v212, 0xa700, v219
	v_mov_b32_e32 v176, 0
	v_mov_b32_e32 v177, 0
	s_add_u32 s98, s26, 0x185a9000
	s_addc_u32 s99, s27, 0
	s_add_u32 s100, s26, 0x1b8a3000
	s_addc_u32 s101, s27, 0
	v_add_u32_e32 v178, 0x1000, v122
	v_add_u32_e32 v179, 0x3000, v122
	v_add_u32_e32 v191, 0x5000, v122
	v_add_u32_e32 v208, 0x44000, v120
	s_getreg_b32 s0, hwreg(HW_REG_HW_ID, 0, 1)
	s_cmp_eq_u32 s0, 0
	s_cbranch_scc1 .Lattprio_skip
	s_setprio 1
